# v54: v50 + 36 B of s_nop at the scan exit so code after P3c sits at the same offset mod 64 as in v40 (placement test)
# speedup vs baseline: 1.0050x; 1.0050x over previous
; __device__ __forceinline__ void xcd_barrier(const XcdBarrier& b) {
;     asm volatile("s_waitcnt vmcnt(0)" ::: "memory");
;     __syncthreads();
;     if (threadIdx.x == 0) {
;         unsigned* bar = b.bar;
;         __builtin_amdgcn_s_waitcnt(0);
;         unsigned nloc = b.st[0], nx = b.st[1];
;         if (nloc == 0u) { xcd_barrier_complete(bar, b.x, nloc, nx); b.st[0] = nloc; b.st[1] = nx; }
; __device__ __forceinline__ void p3_gla_scan(LAS unsigned char* lds_, const Params& p) {
;     ...
;         asm volatile("s_waitcnt vmcnt(0)" ::: "memory");
;     ...
;     }
;     __syncthreads();
.LBB0_628:
	s_nop 0
	s_nop 0
	s_nop 0
	s_nop 0
	s_nop 0
	s_nop 0
	s_nop 0
	s_nop 0
	s_nop 0
	s_waitcnt lgkmcnt(0)
	s_barrier
	s_waitcnt vmcnt(0)
	s_barrier
	s_and_saveexec_b64 s[0:1], s[50:51]
	v_readlane_b32 s72, v247, 25
	v_readlane_b32 s76, v247, 21
	v_readlane_b32 s73, v247, 26
	v_readlane_b32 s77, v247, 22
	s_cbranch_execz .LBB0_680
	s_add_i32 s4, 0, 0x26020
	v_mov_b32_e32 v1, s4
	s_waitcnt vmcnt(0) expcnt(0) lgkmcnt(0)
	ds_read_b32 v3, v1
	s_add_i32 s4, 0, 0x26024
	v_mov_b32_e32 v1, s4
	ds_read_b32 v1, v1
	s_waitcnt lgkmcnt(1)
	v_cmp_ne_u32_e32 vcc, 0, v3
	s_cbranch_vccnz .LBB0_644
	v_readlane_b32 s4, v247, 0
	v_readlane_b32 s5, v247, 1
	s_load_dwordx2 s[8:9], s[4:5], 0x4
	s_add_u32 s4, s96, 0x4200
	s_addc_u32 s5, s97, 0
	s_add_u32 s6, s96, 0x4400
	s_addc_u32 s7, s97, 0
	s_waitcnt lgkmcnt(0)
	s_mul_i32 s33, s8, s60
	s_add_u32 s8, s96, 0x4500
	s_mul_i32 s33, s33, s9
	s_addc_u32 s9, s97, 0
	s_add_u32 s10, s96, 0x4600
	s_addc_u32 s11, s97, 0
	s_add_u32 s12, s96, 0x4700
	s_addc_u32 s13, s97, 0
	s_add_u32 s14, s96, 0x4800
	s_addc_u32 s15, s97, 0
	s_add_u32 s16, s96, 0x4900
	s_addc_u32 s17, s97, 0
	s_add_u32 s18, s96, 0x4a00
	s_addc_u32 s19, s97, 0
	s_add_u32 s20, s96, 0x4b00
	s_addc_u32 s21, s97, 0
	s_add_u32 s22, s96, 0x4c00
	s_addc_u32 s23, s97, 0
	s_add_u32 s24, s96, 0x4d00
	s_addc_u32 s25, s97, 0
	s_add_u32 s26, s96, 0x4e00
	s_addc_u32 s27, s97, 0
	s_add_u32 s28, s96, 0x4f00
	s_addc_u32 s29, s97, 0
	s_add_u32 s30, s96, 0x5000
	s_addc_u32 s31, s97, 0
	s_add_u32 s34, s96, 0x5100
	s_addc_u32 s35, s97, 0
	s_add_u32 s36, s96, 0x5200
	s_addc_u32 s37, s97, 0
	s_add_u32 s38, s96, 0x5300
	s_addc_u32 s39, s97, 0
	s_mov_b32 s46, 1
	v_mov_b32_e32 v17, 0
	s_branch .LBB0_632
